# GEMM loop: s_setprio 1 only across the LDS-DMA issue gaps of the post-barrier half (narrowed static-priority window)
# baseline (speedup 1.0000x reference)
.Lg92_loop:
	s_setprio 0
	s_waitcnt lgkmcnt(0)
	v_mfma_f32_32x32x16_bf16 v[114:129], v[162:165], v[228:231], v[114:129]
	ds_read_b128 v[166:169], v136 offset:0
	ds_read_b128 v[232:235], v137 offset:0
	s_add_i32 s9, s9, 1
	s_add_i32 s14, s9, 2
	s_lshl_b64 s[12:13], s[14:15], 14
	s_add_u32 s12, s12, s74
	s_addc_u32 s13, s13, s75
	v_mfma_f32_32x32x16_bf16 v[98:113], v[162:165], v[236:239], v[98:113]
	ds_read_b128 v[240:243], v137 offset:2048
	ds_read_b128 v[208:211], v136 offset:2048
	v_mfma_f32_32x32x16_bf16 v[82:97], v[204:207], v[228:231], v[82:97]
	ds_read_b128 v[216:219], v136 offset:4096
	ds_read_b128 v[224:227], v136 offset:6144
	v_mfma_f32_32x32x16_bf16 v[66:81], v[204:207], v[236:239], v[66:81]
	v_mfma_f32_32x32x16_bf16 v[50:65], v[212:215], v[228:231], v[50:65]
	v_mfma_f32_32x32x16_bf16 v[34:49], v[212:215], v[236:239], v[34:49]
	v_mfma_f32_32x32x16_bf16 v[18:33], v[220:223], v[228:231], v[18:33]
	v_mfma_f32_32x32x16_bf16 v[2:17], v[220:223], v[236:239], v[2:17]
	s_waitcnt vmcnt(6) lgkmcnt(0)
	s_barrier
	s_add_u32 m0, s34, s72
	s_mov_b32 s34, s73
	s_add_u32 s73, s34, 0x6000
	s_cmp_lt_u32 s73, 0x12000
	s_cselect_b32 s73, s73, 0
	v_mfma_f32_32x32x16_bf16 v[114:129], v[166:169], v[232:235], v[114:129]
	ds_read_b128 v[162:165], v138 offset:0
	ds_read_b128 v[228:231], v139 offset:0
	v_mfma_f32_32x32x16_bf16 v[98:113], v[166:169], v[240:243], v[98:113]
	ds_read_b128 v[236:239], v139 offset:2048
	ds_read_b128 v[204:207], v138 offset:2048
	v_add_u32_e32 v136, s34, v134
	v_add_u32_e32 v137, s34, v135
	v_mfma_f32_32x32x16_bf16 v[82:97], v[208:211], v[232:235], v[82:97]
	ds_read_b128 v[212:215], v138 offset:4096
	ds_read_b128 v[220:223], v138 offset:6144
	s_setprio 1
	v_mfma_f32_32x32x16_bf16 v[66:81], v[208:211], v[240:243], v[66:81]
	global_load_lds_dwordx4 v140, s[12:13]
	s_add_u32 m0, m0, 0x1000
	s_add_u32 s12, s12, 0x1000
	s_addc_u32 s13, s13, 0
	v_add_u32_e32 v138, s73, v132
	v_add_u32_e32 v139, s73, v133
	v_mfma_f32_32x32x16_bf16 v[50:65], v[216:219], v[232:235], v[50:65]
	global_load_lds_dwordx4 v140, s[12:13]
	s_add_u32 m0, m0, 0x1000
	s_add_u32 s12, s12, 0x1000
	s_addc_u32 s13, s13, 0
	v_mfma_f32_32x32x16_bf16 v[34:49], v[216:219], v[240:243], v[34:49]
	global_load_lds_dwordx4 v140, s[12:13]
	s_add_u32 m0, m0, 0x1000
	s_add_u32 s12, s12, 0x1000
	s_addc_u32 s13, s13, 0
	v_mfma_f32_32x32x16_bf16 v[18:33], v[224:227], v[232:235], v[18:33]
	global_load_lds_dwordx4 v140, s[12:13]
	s_add_u32 m0, m0, 0x1000
	s_lshl_b64 s[12:13], s[14:15], 13
	s_add_u32 s12, s12, s76
	s_addc_u32 s13, s13, s77
	v_mfma_f32_32x32x16_bf16 v[2:17], v[224:227], v[240:243], v[2:17]
	global_load_lds_dwordx4 v140, s[12:13]
	s_add_u32 m0, m0, 0x1000
	s_add_u32 s12, s12, 0x1000
	s_addc_u32 s13, s13, 0
	s_nop 0
	global_load_lds_dwordx4 v140, s[12:13]
	s_cmp_lg_u32 s9, 29
	s_cbranch_scc1 .Lg92_loop
	s_setprio 0
	s_waitcnt lgkmcnt(0)
	v_mfma_f32_32x32x16_bf16 v[114:129], v[162:165], v[228:231], v[114:129]
	ds_read_b128 v[166:169], v136 offset:0
	ds_read_b128 v[232:235], v137 offset:0
	s_add_i32 s9, s9, 1
	v_mfma_f32_32x32x16_bf16 v[98:113], v[162:165], v[236:239], v[98:113]
	ds_read_b128 v[240:243], v137 offset:2048
	ds_read_b128 v[208:211], v136 offset:2048
	v_mfma_f32_32x32x16_bf16 v[82:97], v[204:207], v[228:231], v[82:97]
	ds_read_b128 v[216:219], v136 offset:4096
	ds_read_b128 v[224:227], v136 offset:6144
	v_mfma_f32_32x32x16_bf16 v[66:81], v[204:207], v[236:239], v[66:81]
	v_mfma_f32_32x32x16_bf16 v[50:65], v[212:215], v[228:231], v[50:65]
	v_mfma_f32_32x32x16_bf16 v[34:49], v[212:215], v[236:239], v[34:49]
	v_mfma_f32_32x32x16_bf16 v[18:33], v[220:223], v[228:231], v[18:33]
	v_mfma_f32_32x32x16_bf16 v[2:17], v[220:223], v[236:239], v[2:17]
	s_waitcnt vmcnt(6) lgkmcnt(0)
	s_barrier
	s_mov_b32 s34, s73
	s_add_u32 s73, s34, 0x6000
	s_cmp_lt_u32 s73, 0x12000
	s_cselect_b32 s73, s73, 0
	v_mfma_f32_32x32x16_bf16 v[114:129], v[166:169], v[232:235], v[114:129]
	ds_read_b128 v[162:165], v138 offset:0
	ds_read_b128 v[228:231], v139 offset:0
	v_mfma_f32_32x32x16_bf16 v[98:113], v[166:169], v[240:243], v[98:113]
	ds_read_b128 v[236:239], v139 offset:2048
	ds_read_b128 v[204:207], v138 offset:2048
	v_add_u32_e32 v136, s34, v134
	v_add_u32_e32 v137, s34, v135
	v_mfma_f32_32x32x16_bf16 v[82:97], v[208:211], v[232:235], v[82:97]
	ds_read_b128 v[212:215], v138 offset:4096
	ds_read_b128 v[220:223], v138 offset:6144
	v_mfma_f32_32x32x16_bf16 v[66:81], v[208:211], v[240:243], v[66:81]
	v_add_u32_e32 v138, s73, v132
	v_add_u32_e32 v139, s73, v133
	v_mfma_f32_32x32x16_bf16 v[50:65], v[216:219], v[232:235], v[50:65]
	v_mfma_f32_32x32x16_bf16 v[34:49], v[216:219], v[240:243], v[34:49]
	v_mfma_f32_32x32x16_bf16 v[18:33], v[224:227], v[232:235], v[18:33]
	v_mfma_f32_32x32x16_bf16 v[2:17], v[224:227], v[240:243], v[2:17]
	s_setprio 0
	s_waitcnt lgkmcnt(0)
	v_mfma_f32_32x32x16_bf16 v[114:129], v[162:165], v[228:231], v[114:129]
	ds_read_b128 v[166:169], v136 offset:0
	ds_read_b128 v[232:235], v137 offset:0
	s_add_i32 s9, s9, 1
	v_mfma_f32_32x32x16_bf16 v[98:113], v[162:165], v[236:239], v[98:113]
	ds_read_b128 v[240:243], v137 offset:2048
	ds_read_b128 v[208:211], v136 offset:2048
	v_mfma_f32_32x32x16_bf16 v[82:97], v[204:207], v[228:231], v[82:97]
	ds_read_b128 v[216:219], v136 offset:4096
	ds_read_b128 v[224:227], v136 offset:6144
	v_mfma_f32_32x32x16_bf16 v[66:81], v[204:207], v[236:239], v[66:81]
	v_mfma_f32_32x32x16_bf16 v[50:65], v[212:215], v[228:231], v[50:65]
	v_mfma_f32_32x32x16_bf16 v[34:49], v[212:215], v[236:239], v[34:49]
	v_mfma_f32_32x32x16_bf16 v[18:33], v[220:223], v[228:231], v[18:33]
	v_mfma_f32_32x32x16_bf16 v[2:17], v[220:223], v[236:239], v[2:17]
	s_waitcnt vmcnt(0) lgkmcnt(0)
	s_barrier
	s_mov_b32 s34, s73
	s_add_u32 s73, s34, 0x6000
	s_cmp_lt_u32 s73, 0x12000
	s_cselect_b32 s73, s73, 0
	v_mfma_f32_32x32x16_bf16 v[114:129], v[166:169], v[232:235], v[114:129]
	ds_read_b128 v[162:165], v138 offset:0
	ds_read_b128 v[228:231], v139 offset:0
	v_mfma_f32_32x32x16_bf16 v[98:113], v[166:169], v[240:243], v[98:113]
	ds_read_b128 v[236:239], v139 offset:2048
	ds_read_b128 v[204:207], v138 offset:2048
	v_add_u32_e32 v136, s34, v134
	v_add_u32_e32 v137, s34, v135
	v_mfma_f32_32x32x16_bf16 v[82:97], v[208:211], v[232:235], v[82:97]
	ds_read_b128 v[212:215], v138 offset:4096
	ds_read_b128 v[220:223], v138 offset:6144
	v_mfma_f32_32x32x16_bf16 v[66:81], v[208:211], v[240:243], v[66:81]
	v_add_u32_e32 v138, s73, v132
	v_add_u32_e32 v139, s73, v133
	v_mfma_f32_32x32x16_bf16 v[50:65], v[216:219], v[232:235], v[50:65]
	v_mfma_f32_32x32x16_bf16 v[34:49], v[216:219], v[240:243], v[34:49]
	v_mfma_f32_32x32x16_bf16 v[18:33], v[224:227], v[232:235], v[18:33]
	v_mfma_f32_32x32x16_bf16 v[2:17], v[224:227], v[240:243], v[2:17]
	s_setprio 0
	s_waitcnt lgkmcnt(0)
	v_mfma_f32_32x32x16_bf16 v[114:129], v[162:165], v[228:231], v[114:129]
	ds_read_b128 v[166:169], v136 offset:0
	ds_read_b128 v[232:235], v137 offset:0
	s_add_i32 s9, s9, 1
	v_mfma_f32_32x32x16_bf16 v[98:113], v[162:165], v[236:239], v[98:113]
	ds_read_b128 v[240:243], v137 offset:2048
	ds_read_b128 v[208:211], v136 offset:2048
	v_mfma_f32_32x32x16_bf16 v[82:97], v[204:207], v[228:231], v[82:97]
	ds_read_b128 v[216:219], v136 offset:4096
	ds_read_b128 v[224:227], v136 offset:6144
	v_mfma_f32_32x32x16_bf16 v[66:81], v[204:207], v[236:239], v[66:81]
	v_mfma_f32_32x32x16_bf16 v[50:65], v[212:215], v[228:231], v[50:65]
	v_mfma_f32_32x32x16_bf16 v[34:49], v[212:215], v[236:239], v[34:49]
	v_mfma_f32_32x32x16_bf16 v[18:33], v[220:223], v[228:231], v[18:33]
	v_mfma_f32_32x32x16_bf16 v[2:17], v[220:223], v[236:239], v[2:17]
	s_waitcnt lgkmcnt(0)
	v_mfma_f32_32x32x16_bf16 v[114:129], v[166:169], v[232:235], v[114:129]
	v_mfma_f32_32x32x16_bf16 v[98:113], v[166:169], v[240:243], v[98:113]
	v_mfma_f32_32x32x16_bf16 v[82:97], v[208:211], v[232:235], v[82:97]
	v_mfma_f32_32x32x16_bf16 v[66:81], v[208:211], v[240:243], v[66:81]
	v_mfma_f32_32x32x16_bf16 v[50:65], v[216:219], v[232:235], v[50:65]
	v_mfma_f32_32x32x16_bf16 v[34:49], v[216:219], v[240:243], v[34:49]
	v_mfma_f32_32x32x16_bf16 v[18:33], v[224:227], v[232:235], v[18:33]
	v_mfma_f32_32x32x16_bf16 v[2:17], v[224:227], v[240:243], v[2:17]
	s_mov_b32 s14, 31
	s_lshl_b64 s[12:13], s[14:15], 13
	s_movk_i32 s34, 0x7800
	s_movk_i32 s72, 0x6000
	s_mov_b32 s73, 0xc000
	s_setprio 0
	s_movk_i32 s74, 0x104
	s_mov_b32 s75, 0x42ce8ed0
	s_mov_b32 s76, 0xbfb8aa3b
	s_mov_b32 s77, 0x1d730000
	v_mov_b32_e32 v0, v171
	s_barrier
	s_waitcnt vmcnt(4)
	v_lshrrev_b32_e32 v130, 1, v0
	v_and_b32_e32 v130, 0xfffffc0, v130
	v_lshrrev_b32_e32 v131, 3, v0
	v_and_or_b32 v130, v131, 4, v130
	v_and_b32_e32 v0, 0x5f, v0
	v_mul_lo_u32 v130, v130, s53
	v_lshl_add_u32 v0, v0, 2, v130
	s_barrier
	ds_write2_b32 v0, v114, v98 offset1:32
	ds_write2_b32 v0, v115, v99 offset0:132 offset1:164
	v_add_u32_e32 v98, 0x400, v0
	ds_write2_b32 v98, v116, v100 offset0:8 offset1:40
	ds_write2_b32 v98, v117, v101 offset0:140 offset1:172
	v_add_u32_e32 v98, 0x1000, v0
	ds_write2_b32 v98, v118, v102 offset0:32 offset1:64
	ds_write2_b32 v98, v119, v103 offset0:164 offset1:196
	v_add_u32_e32 v98, 0x1400, v0
	ds_write2_b32 v98, v120, v104 offset0:40 offset1:72
	ds_write2_b32 v98, v121, v105 offset0:172 offset1:204
	v_add_u32_e32 v98, 0x2000, v0
	ds_write2_b32 v98, v122, v106 offset0:64 offset1:96
	ds_write2_b32 v98, v123, v107 offset0:196 offset1:228
	v_add_u32_e32 v98, 0x2400, v0
	ds_write2_b32 v98, v124, v108 offset0:72 offset1:104
	ds_write2_b32 v98, v125, v109 offset0:204 offset1:236
	v_add_u32_e32 v98, 0x3000, v0
	ds_write2_b32 v98, v126, v110 offset0:96 offset1:128
	v_add_u32_e32 v98, 0x3200, v0
	ds_write2_b32 v98, v127, v111 offset0:100 offset1:132
	v_add_u32_e32 v98, 0x3400, v0
	ds_write2_b32 v98, v128, v112 offset0:104 offset1:136
	v_add_u32_e32 v98, 0x3600, v0
	ds_write2_b32 v98, v129, v113 offset0:108 offset1:140
	v_add_u32_e32 v98, 0x4000, v0
	ds_write2_b32 v98, v82, v66 offset0:128 offset1:160
	v_add_u32_e32 v66, 0x4400, v0
	ds_write2_b32 v66, v83, v67 offset0:4 offset1:36
	ds_write2_b32 v66, v84, v68 offset0:136 offset1:168
	v_add_u32_e32 v66, 0x4800, v0
	ds_write2_b32 v66, v85, v69 offset0:12 offset1:44
	v_add_u32_e32 v66, 0x5000, v0
	ds_write2_b32 v66, v86, v70 offset0:160 offset1:192
	v_add_u32_e32 v66, 0x5400, v0
	ds_write2_b32 v66, v87, v71 offset0:36 offset1:68
	ds_write2_b32 v66, v88, v72 offset0:168 offset1:200
	v_add_u32_e32 v66, 0x5800, v0
	ds_write2_b32 v66, v89, v73 offset0:44 offset1:76
	v_add_u32_e32 v66, 0x6000, v0
	ds_write2_b32 v66, v90, v74 offset0:192 offset1:224
	v_add_u32_e32 v66, 0x6400, v0
	ds_write2_b32 v66, v91, v75 offset0:68 offset1:100
	ds_write2_b32 v66, v92, v76 offset0:200 offset1:232
	v_add_u32_e32 v66, 0x6800, v0
	ds_write2_b32 v66, v93, v77 offset0:76 offset1:108
	v_add_u32_e32 v66, 0x7200, v0
	ds_write2_b32 v66, v94, v78 offset0:96 offset1:128
	v_add_u32_e32 v66, 0x7400, v0
	ds_write2_b32 v66, v95, v79 offset0:100 offset1:132
	v_add_u32_e32 v66, 0x7600, v0
	v_add_u32_e32 v0, 0x7800, v0
	v_mov_b32_e32 v74, v171
	ds_write2_b32 v66, v96, v80 offset0:104 offset1:136
	ds_write2_b32 v0, v97, v81 offset0:108 offset1:140
	s_waitcnt lgkmcnt(0)
	s_barrier
	s_lshl_b32 s8, s8, 7
	v_lshlrev_b32_e32 v75, 3, v74
	v_and_b32_e32 v0, 0x78, v75
	v_or_b32_e32 v0, s8, v0
	v_lshl_add_u64 v[70:71], v[0:1], 2, s[6:7]
	global_load_dwordx4 v[66:69], v[70:71], off
	s_nop 0
	global_load_dwordx4 v[70:73], v[70:71], off offset:16
	v_ashrrev_i32_e32 v76, 4, v74
	v_lshrrev_b32_e32 v77, 5, v0
	v_and_b32_e32 v0, 24, v75
	v_mul_lo_u32 v75, v76, s53
	v_and_b32_e32 v74, 15, v74
	v_readlane_b32 s0, v252, 46
	s_lshl_b32 s9, s11, 8
	v_lshl_add_u32 v78, v74, 5, v75
	v_lshlrev_b32_e32 v79, 1, v76
	s_mov_b32 s11, 0
	v_lshlrev_b32_e32 v74, 1, v0
	v_readlane_b32 s1, v252, 47
	s_waitcnt vmcnt(0)

.Lg357_loop:
	s_setprio 0
	s_waitcnt lgkmcnt(0)
	v_mfma_f32_32x32x16_bf16 v[114:129], v[162:165], v[228:231], v[114:129]
	ds_read_b128 v[166:169], v136 offset:0
	ds_read_b128 v[232:235], v137 offset:0
	s_add_i32 s7, s7, 1
	s_add_i32 s14, s7, 2
	s_lshl_b64 s[10:11], s[14:15], 14
	s_add_u32 s10, s10, s74
	s_addc_u32 s11, s11, s75
	v_mfma_f32_32x32x16_bf16 v[98:113], v[162:165], v[236:239], v[98:113]
	ds_read_b128 v[240:243], v137 offset:2048
	ds_read_b128 v[208:211], v136 offset:2048
	v_mfma_f32_32x32x16_bf16 v[82:97], v[204:207], v[228:231], v[82:97]
	ds_read_b128 v[216:219], v136 offset:4096
	ds_read_b128 v[224:227], v136 offset:6144
	v_mfma_f32_32x32x16_bf16 v[66:81], v[204:207], v[236:239], v[66:81]
	v_mfma_f32_32x32x16_bf16 v[50:65], v[212:215], v[228:231], v[50:65]
	v_mfma_f32_32x32x16_bf16 v[34:49], v[212:215], v[236:239], v[34:49]
	v_mfma_f32_32x32x16_bf16 v[18:33], v[220:223], v[228:231], v[18:33]
	v_mfma_f32_32x32x16_bf16 v[2:17], v[220:223], v[236:239], v[2:17]
	s_waitcnt vmcnt(6) lgkmcnt(0)
	s_barrier
	s_add_u32 m0, s13, s72
	s_mov_b32 s13, s73
	s_add_u32 s73, s13, 0x6000
	s_cmp_lt_u32 s73, 0x12000
	s_cselect_b32 s73, s73, 0
	v_mfma_f32_32x32x16_bf16 v[114:129], v[166:169], v[232:235], v[114:129]
	ds_read_b128 v[162:165], v138 offset:0
	ds_read_b128 v[228:231], v139 offset:0
	v_mfma_f32_32x32x16_bf16 v[98:113], v[166:169], v[240:243], v[98:113]
	ds_read_b128 v[236:239], v139 offset:2048
	ds_read_b128 v[204:207], v138 offset:2048
	v_add_u32_e32 v136, s13, v134
	v_add_u32_e32 v137, s13, v135
	v_mfma_f32_32x32x16_bf16 v[82:97], v[208:211], v[232:235], v[82:97]
	ds_read_b128 v[212:215], v138 offset:4096
	ds_read_b128 v[220:223], v138 offset:6144
	s_setprio 1
	v_mfma_f32_32x32x16_bf16 v[66:81], v[208:211], v[240:243], v[66:81]
	global_load_lds_dwordx4 v140, s[10:11]
	s_add_u32 m0, m0, 0x1000
	s_add_u32 s10, s10, 0x1000
	s_addc_u32 s11, s11, 0
	v_add_u32_e32 v138, s73, v132
	v_add_u32_e32 v139, s73, v133
	v_mfma_f32_32x32x16_bf16 v[50:65], v[216:219], v[232:235], v[50:65]
	global_load_lds_dwordx4 v140, s[10:11]
	s_add_u32 m0, m0, 0x1000
	s_add_u32 s10, s10, 0x1000
	s_addc_u32 s11, s11, 0
	v_mfma_f32_32x32x16_bf16 v[34:49], v[216:219], v[240:243], v[34:49]
	global_load_lds_dwordx4 v140, s[10:11]
	s_add_u32 m0, m0, 0x1000
	s_add_u32 s10, s10, 0x1000
	s_addc_u32 s11, s11, 0
	v_mfma_f32_32x32x16_bf16 v[18:33], v[224:227], v[232:235], v[18:33]
	global_load_lds_dwordx4 v140, s[10:11]
	s_add_u32 m0, m0, 0x1000
	s_lshl_b64 s[10:11], s[14:15], 13
	s_add_u32 s10, s10, s76
	s_addc_u32 s11, s11, s77
	v_mfma_f32_32x32x16_bf16 v[2:17], v[224:227], v[240:243], v[2:17]
	global_load_lds_dwordx4 v140, s[10:11]
	s_add_u32 m0, m0, 0x1000
	s_add_u32 s10, s10, 0x1000
	s_addc_u32 s11, s11, 0
	s_nop 0
	global_load_lds_dwordx4 v140, s[10:11]
	s_cmp_lg_u32 s7, 29
	s_cbranch_scc1 .Lg357_loop
	s_setprio 0
	s_waitcnt lgkmcnt(0)
	v_mfma_f32_32x32x16_bf16 v[114:129], v[162:165], v[228:231], v[114:129]
	ds_read_b128 v[166:169], v136 offset:0
	ds_read_b128 v[232:235], v137 offset:0
	s_add_i32 s7, s7, 1
	v_mfma_f32_32x32x16_bf16 v[98:113], v[162:165], v[236:239], v[98:113]
	ds_read_b128 v[240:243], v137 offset:2048
	ds_read_b128 v[208:211], v136 offset:2048
	v_mfma_f32_32x32x16_bf16 v[82:97], v[204:207], v[228:231], v[82:97]
	ds_read_b128 v[216:219], v136 offset:4096
	ds_read_b128 v[224:227], v136 offset:6144
	v_mfma_f32_32x32x16_bf16 v[66:81], v[204:207], v[236:239], v[66:81]
	v_mfma_f32_32x32x16_bf16 v[50:65], v[212:215], v[228:231], v[50:65]
	v_mfma_f32_32x32x16_bf16 v[34:49], v[212:215], v[236:239], v[34:49]
	v_mfma_f32_32x32x16_bf16 v[18:33], v[220:223], v[228:231], v[18:33]
	v_mfma_f32_32x32x16_bf16 v[2:17], v[220:223], v[236:239], v[2:17]
	s_waitcnt vmcnt(6) lgkmcnt(0)
	s_barrier
	s_mov_b32 s13, s73
	s_add_u32 s73, s13, 0x6000
	s_cmp_lt_u32 s73, 0x12000
	s_cselect_b32 s73, s73, 0
	v_mfma_f32_32x32x16_bf16 v[114:129], v[166:169], v[232:235], v[114:129]
	ds_read_b128 v[162:165], v138 offset:0
	ds_read_b128 v[228:231], v139 offset:0
	v_mfma_f32_32x32x16_bf16 v[98:113], v[166:169], v[240:243], v[98:113]
	ds_read_b128 v[236:239], v139 offset:2048
	ds_read_b128 v[204:207], v138 offset:2048
	v_add_u32_e32 v136, s13, v134
	v_add_u32_e32 v137, s13, v135
	v_mfma_f32_32x32x16_bf16 v[82:97], v[208:211], v[232:235], v[82:97]
	ds_read_b128 v[212:215], v138 offset:4096
	ds_read_b128 v[220:223], v138 offset:6144
	v_mfma_f32_32x32x16_bf16 v[66:81], v[208:211], v[240:243], v[66:81]
	v_add_u32_e32 v138, s73, v132
	v_add_u32_e32 v139, s73, v133
	v_mfma_f32_32x32x16_bf16 v[50:65], v[216:219], v[232:235], v[50:65]
	v_mfma_f32_32x32x16_bf16 v[34:49], v[216:219], v[240:243], v[34:49]
	v_mfma_f32_32x32x16_bf16 v[18:33], v[224:227], v[232:235], v[18:33]
	v_mfma_f32_32x32x16_bf16 v[2:17], v[224:227], v[240:243], v[2:17]
	s_setprio 0
	s_waitcnt lgkmcnt(0)
	v_mfma_f32_32x32x16_bf16 v[114:129], v[162:165], v[228:231], v[114:129]
	ds_read_b128 v[166:169], v136 offset:0
	ds_read_b128 v[232:235], v137 offset:0
	s_add_i32 s7, s7, 1
	v_mfma_f32_32x32x16_bf16 v[98:113], v[162:165], v[236:239], v[98:113]
	ds_read_b128 v[240:243], v137 offset:2048
	ds_read_b128 v[208:211], v136 offset:2048
	v_mfma_f32_32x32x16_bf16 v[82:97], v[204:207], v[228:231], v[82:97]
	ds_read_b128 v[216:219], v136 offset:4096
	ds_read_b128 v[224:227], v136 offset:6144
	v_mfma_f32_32x32x16_bf16 v[66:81], v[204:207], v[236:239], v[66:81]
	v_mfma_f32_32x32x16_bf16 v[50:65], v[212:215], v[228:231], v[50:65]
	v_mfma_f32_32x32x16_bf16 v[34:49], v[212:215], v[236:239], v[34:49]
	v_mfma_f32_32x32x16_bf16 v[18:33], v[220:223], v[228:231], v[18:33]
	v_mfma_f32_32x32x16_bf16 v[2:17], v[220:223], v[236:239], v[2:17]
	s_waitcnt vmcnt(0) lgkmcnt(0)
	s_barrier
	s_mov_b32 s13, s73
	s_add_u32 s73, s13, 0x6000
	s_cmp_lt_u32 s73, 0x12000
	s_cselect_b32 s73, s73, 0
	v_mfma_f32_32x32x16_bf16 v[114:129], v[166:169], v[232:235], v[114:129]
	ds_read_b128 v[162:165], v138 offset:0
	ds_read_b128 v[228:231], v139 offset:0
	v_mfma_f32_32x32x16_bf16 v[98:113], v[166:169], v[240:243], v[98:113]
	ds_read_b128 v[236:239], v139 offset:2048
	ds_read_b128 v[204:207], v138 offset:2048
	v_add_u32_e32 v136, s13, v134
	v_add_u32_e32 v137, s13, v135
	v_mfma_f32_32x32x16_bf16 v[82:97], v[208:211], v[232:235], v[82:97]
	ds_read_b128 v[212:215], v138 offset:4096
	ds_read_b128 v[220:223], v138 offset:6144
	v_mfma_f32_32x32x16_bf16 v[66:81], v[208:211], v[240:243], v[66:81]
	v_add_u32_e32 v138, s73, v132
	v_add_u32_e32 v139, s73, v133
	v_mfma_f32_32x32x16_bf16 v[50:65], v[216:219], v[232:235], v[50:65]
	v_mfma_f32_32x32x16_bf16 v[34:49], v[216:219], v[240:243], v[34:49]
	v_mfma_f32_32x32x16_bf16 v[18:33], v[224:227], v[232:235], v[18:33]
	v_mfma_f32_32x32x16_bf16 v[2:17], v[224:227], v[240:243], v[2:17]
	s_setprio 0
	s_waitcnt lgkmcnt(0)
	v_mfma_f32_32x32x16_bf16 v[114:129], v[162:165], v[228:231], v[114:129]
	ds_read_b128 v[166:169], v136 offset:0
	ds_read_b128 v[232:235], v137 offset:0
	s_add_i32 s7, s7, 1
	v_mfma_f32_32x32x16_bf16 v[98:113], v[162:165], v[236:239], v[98:113]
	ds_read_b128 v[240:243], v137 offset:2048
	ds_read_b128 v[208:211], v136 offset:2048
	v_mfma_f32_32x32x16_bf16 v[82:97], v[204:207], v[228:231], v[82:97]
	ds_read_b128 v[216:219], v136 offset:4096
	ds_read_b128 v[224:227], v136 offset:6144
	v_mfma_f32_32x32x16_bf16 v[66:81], v[204:207], v[236:239], v[66:81]
	v_mfma_f32_32x32x16_bf16 v[50:65], v[212:215], v[228:231], v[50:65]
	v_mfma_f32_32x32x16_bf16 v[34:49], v[212:215], v[236:239], v[34:49]
	v_mfma_f32_32x32x16_bf16 v[18:33], v[220:223], v[228:231], v[18:33]
	v_mfma_f32_32x32x16_bf16 v[2:17], v[220:223], v[236:239], v[2:17]
	s_waitcnt lgkmcnt(0)
	v_mfma_f32_32x32x16_bf16 v[114:129], v[166:169], v[232:235], v[114:129]
	v_mfma_f32_32x32x16_bf16 v[98:113], v[166:169], v[240:243], v[98:113]
	v_mfma_f32_32x32x16_bf16 v[82:97], v[208:211], v[232:235], v[82:97]
	v_mfma_f32_32x32x16_bf16 v[66:81], v[208:211], v[240:243], v[66:81]
	v_mfma_f32_32x32x16_bf16 v[50:65], v[216:219], v[232:235], v[50:65]
	v_mfma_f32_32x32x16_bf16 v[34:49], v[216:219], v[240:243], v[34:49]
	v_mfma_f32_32x32x16_bf16 v[18:33], v[224:227], v[232:235], v[18:33]
	v_mfma_f32_32x32x16_bf16 v[2:17], v[224:227], v[240:243], v[2:17]
	s_mov_b32 s14, 31
	s_lshl_b64 s[10:11], s[14:15], 13
	s_movk_i32 s13, 0x7800
	s_movk_i32 s72, 0x6000
	s_mov_b32 s73, 0xc000
	s_setprio 0
	s_movk_i32 s74, 0x104
	s_mov_b32 s75, 0x42ce8ed0
	s_mov_b32 s76, 0xbfb8aa3b
	s_mov_b32 s77, 0x1d730000
	v_mov_b32_e32 v0, v171
	s_barrier
	s_waitcnt vmcnt(4)
	v_lshrrev_b32_e32 v130, 1, v0
	v_and_b32_e32 v130, 0xfffffc0, v130
	v_lshrrev_b32_e32 v131, 3, v0
	v_and_or_b32 v130, v131, 4, v130
	v_and_b32_e32 v0, 0x5f, v0
	v_mul_lo_u32 v130, v130, s53
	v_lshl_add_u32 v0, v0, 2, v130
	s_barrier
	ds_write2_b32 v0, v114, v98 offset1:32
	ds_write2_b32 v0, v115, v99 offset0:132 offset1:164
	v_add_u32_e32 v98, 0x400, v0
	ds_write2_b32 v98, v116, v100 offset0:8 offset1:40
	ds_write2_b32 v98, v117, v101 offset0:140 offset1:172
	v_add_u32_e32 v98, 0x1000, v0
	ds_write2_b32 v98, v118, v102 offset0:32 offset1:64
	ds_write2_b32 v98, v119, v103 offset0:164 offset1:196
	v_add_u32_e32 v98, 0x1400, v0
	ds_write2_b32 v98, v120, v104 offset0:40 offset1:72
	ds_write2_b32 v98, v121, v105 offset0:172 offset1:204
	v_add_u32_e32 v98, 0x2000, v0
	ds_write2_b32 v98, v122, v106 offset0:64 offset1:96
	ds_write2_b32 v98, v123, v107 offset0:196 offset1:228
	v_add_u32_e32 v98, 0x2400, v0
	ds_write2_b32 v98, v124, v108 offset0:72 offset1:104
	ds_write2_b32 v98, v125, v109 offset0:204 offset1:236
	v_add_u32_e32 v98, 0x3000, v0
	ds_write2_b32 v98, v126, v110 offset0:96 offset1:128
	v_add_u32_e32 v98, 0x3200, v0
	ds_write2_b32 v98, v127, v111 offset0:100 offset1:132
	v_add_u32_e32 v98, 0x3400, v0
	ds_write2_b32 v98, v128, v112 offset0:104 offset1:136
	v_add_u32_e32 v98, 0x3600, v0
	ds_write2_b32 v98, v129, v113 offset0:108 offset1:140
	v_add_u32_e32 v98, 0x4000, v0
	ds_write2_b32 v98, v82, v66 offset0:128 offset1:160
	v_add_u32_e32 v66, 0x4400, v0
	ds_write2_b32 v66, v83, v67 offset0:4 offset1:36
	ds_write2_b32 v66, v84, v68 offset0:136 offset1:168
	v_add_u32_e32 v66, 0x4800, v0
	ds_write2_b32 v66, v85, v69 offset0:12 offset1:44
	v_add_u32_e32 v66, 0x5000, v0
	s_lshl_b32 s13, s9, 8
	ds_write2_b32 v66, v86, v70 offset0:160 offset1:192
	v_add_u32_e32 v66, 0x5400, v0
	s_lshl_b32 s34, s6, 7
	ds_write2_b32 v66, v87, v71 offset0:36 offset1:68
	ds_write2_b32 v66, v88, v72 offset0:168 offset1:200
	v_add_u32_e32 v66, 0x5800, v0
	s_add_i32 s6, s13, 0xffffe000
	ds_write2_b32 v66, v89, v73 offset0:44 offset1:76
	v_add_u32_e32 v66, 0x6000, v0
	s_lshr_b32 s6, s6, 12
	ds_write2_b32 v66, v90, v74 offset0:192 offset1:224
	v_add_u32_e32 v66, 0x6400, v0
	s_mulk_i32 s6, 0x1800
	ds_write2_b32 v66, v91, v75 offset0:68 offset1:100
	ds_write2_b32 v66, v92, v76 offset0:200 offset1:232
	v_add_u32_e32 v66, 0x6800, v0
	s_addk_i32 s6, 0x1800
	ds_write2_b32 v66, v93, v77 offset0:76 offset1:108
	v_add_u32_e32 v66, 0x7200, v0
	s_cmp_gt_u32 s8, 31
	ds_write2_b32 v66, v94, v78 offset0:96 offset1:128
	v_add_u32_e32 v66, 0x7400, v0
	s_cselect_b32 s14, s6, 0
	ds_write2_b32 v66, v95, v79 offset0:100 offset1:132
	v_add_u32_e32 v66, 0x7600, v0
	v_add_u32_e32 v0, 0x7800, v0
	v_mov_b32_e32 v76, v171
	s_lshl_b64 s[6:7], s[14:15], 2
	ds_write2_b32 v66, v96, v80 offset0:104 offset1:136
	ds_write2_b32 v0, v97, v81 offset0:108 offset1:140
	s_waitcnt lgkmcnt(0)
	s_barrier
	s_add_u32 s6, s61, s6
	v_lshlrev_b32_e32 v0, 3, v76
	v_and_b32_e32 v0, 0x78, v0
	s_addc_u32 s7, s79, s7
	v_or_b32_e32 v0, s34, v0
	s_add_u32 s8, s6, 0x1d642000
	s_addc_u32 s9, s7, 0
	v_lshlrev_b64 v[74:75], 2, v[0:1]
	v_lshl_add_u64 v[70:71], s[8:9], 0, v[74:75]
	global_load_dwordx4 v[66:69], v[70:71], off offset:16
	s_nop 0
	global_load_dwordx4 v[70:73], v[70:71], off
	v_ashrrev_i32_e32 v90, 4, v76
	v_lshl_add_u64 v[82:83], s[56:57], 0, v[74:75]
	v_mul_lo_u32 v74, v90, s53
	v_and_b32_e32 v75, 15, v76
	s_mov_b32 s14, 0
	v_lshl_add_u32 v91, v75, 5, v74
	v_lshlrev_b32_e32 v92, 1, v90
	s_branch .LBB0_360

.Lg432_loop:
	s_setprio 0
	s_waitcnt lgkmcnt(0)
	v_mfma_f32_32x32x16_bf16 v[114:129], v[162:165], v[228:231], v[114:129]
	ds_read_b128 v[166:169], v136 offset:0
	ds_read_b128 v[232:235], v137 offset:0
	s_add_i32 s6, s6, 1
	s_add_i32 s14, s6, 2
	s_lshl_b64 s[12:13], s[14:15], 14
	s_add_u32 s12, s12, s74
	s_addc_u32 s13, s13, s75
	v_mfma_f32_32x32x16_bf16 v[98:113], v[162:165], v[236:239], v[98:113]
	ds_read_b128 v[240:243], v137 offset:2048
	ds_read_b128 v[208:211], v136 offset:2048
	v_mfma_f32_32x32x16_bf16 v[82:97], v[204:207], v[228:231], v[82:97]
	ds_read_b128 v[216:219], v136 offset:4096
	ds_read_b128 v[224:227], v136 offset:6144
	v_mfma_f32_32x32x16_bf16 v[66:81], v[204:207], v[236:239], v[66:81]
	v_mfma_f32_32x32x16_bf16 v[50:65], v[212:215], v[228:231], v[50:65]
	v_mfma_f32_32x32x16_bf16 v[34:49], v[212:215], v[236:239], v[34:49]
	v_mfma_f32_32x32x16_bf16 v[18:33], v[220:223], v[228:231], v[18:33]
	v_mfma_f32_32x32x16_bf16 v[2:17], v[220:223], v[236:239], v[2:17]
	s_waitcnt vmcnt(6) lgkmcnt(0)
	s_barrier
	s_add_u32 m0, s7, s72
	s_mov_b32 s7, s73
	s_add_u32 s73, s7, 0x6000
	s_cmp_lt_u32 s73, 0x12000
	s_cselect_b32 s73, s73, 0
	v_mfma_f32_32x32x16_bf16 v[114:129], v[166:169], v[232:235], v[114:129]
	ds_read_b128 v[162:165], v138 offset:0
	ds_read_b128 v[228:231], v139 offset:0
	v_mfma_f32_32x32x16_bf16 v[98:113], v[166:169], v[240:243], v[98:113]
	ds_read_b128 v[236:239], v139 offset:2048
	ds_read_b128 v[204:207], v138 offset:2048
	v_add_u32_e32 v136, s7, v134
	v_add_u32_e32 v137, s7, v135
	v_mfma_f32_32x32x16_bf16 v[82:97], v[208:211], v[232:235], v[82:97]
	ds_read_b128 v[212:215], v138 offset:4096
	ds_read_b128 v[220:223], v138 offset:6144
	s_setprio 1
	v_mfma_f32_32x32x16_bf16 v[66:81], v[208:211], v[240:243], v[66:81]
	global_load_lds_dwordx4 v140, s[12:13]
	s_add_u32 m0, m0, 0x1000
	s_add_u32 s12, s12, 0x1000
	s_addc_u32 s13, s13, 0
	v_add_u32_e32 v138, s73, v132
	v_add_u32_e32 v139, s73, v133
	v_mfma_f32_32x32x16_bf16 v[50:65], v[216:219], v[232:235], v[50:65]
	global_load_lds_dwordx4 v140, s[12:13]
	s_add_u32 m0, m0, 0x1000
	s_add_u32 s12, s12, 0x1000
	s_addc_u32 s13, s13, 0
	v_mfma_f32_32x32x16_bf16 v[34:49], v[216:219], v[240:243], v[34:49]
	global_load_lds_dwordx4 v140, s[12:13]
	s_add_u32 m0, m0, 0x1000
	s_add_u32 s12, s12, 0x1000
	s_addc_u32 s13, s13, 0
	v_mfma_f32_32x32x16_bf16 v[18:33], v[224:227], v[232:235], v[18:33]
	global_load_lds_dwordx4 v140, s[12:13]
	s_add_u32 m0, m0, 0x1000
	s_lshl_b64 s[12:13], s[14:15], 13
	s_add_u32 s12, s12, s76
	s_addc_u32 s13, s13, s77
	v_mfma_f32_32x32x16_bf16 v[2:17], v[224:227], v[240:243], v[2:17]
	global_load_lds_dwordx4 v140, s[12:13]
	s_add_u32 m0, m0, 0x1000
	s_add_u32 s12, s12, 0x1000
	s_addc_u32 s13, s13, 0
	s_nop 0
	global_load_lds_dwordx4 v140, s[12:13]
	s_cmp_lg_u32 s6, 29
	s_cbranch_scc1 .Lg432_loop
	s_setprio 0
	s_waitcnt lgkmcnt(0)
	v_mfma_f32_32x32x16_bf16 v[114:129], v[162:165], v[228:231], v[114:129]
	ds_read_b128 v[166:169], v136 offset:0
	ds_read_b128 v[232:235], v137 offset:0
	s_add_i32 s6, s6, 1
	v_mfma_f32_32x32x16_bf16 v[98:113], v[162:165], v[236:239], v[98:113]
	ds_read_b128 v[240:243], v137 offset:2048
	ds_read_b128 v[208:211], v136 offset:2048
	v_mfma_f32_32x32x16_bf16 v[82:97], v[204:207], v[228:231], v[82:97]
	ds_read_b128 v[216:219], v136 offset:4096
	ds_read_b128 v[224:227], v136 offset:6144
	v_mfma_f32_32x32x16_bf16 v[66:81], v[204:207], v[236:239], v[66:81]
	v_mfma_f32_32x32x16_bf16 v[50:65], v[212:215], v[228:231], v[50:65]
	v_mfma_f32_32x32x16_bf16 v[34:49], v[212:215], v[236:239], v[34:49]
	v_mfma_f32_32x32x16_bf16 v[18:33], v[220:223], v[228:231], v[18:33]
	v_mfma_f32_32x32x16_bf16 v[2:17], v[220:223], v[236:239], v[2:17]
	s_waitcnt vmcnt(6) lgkmcnt(0)
	s_barrier
	s_mov_b32 s7, s73
	s_add_u32 s73, s7, 0x6000
	s_cmp_lt_u32 s73, 0x12000
	s_cselect_b32 s73, s73, 0
	v_mfma_f32_32x32x16_bf16 v[114:129], v[166:169], v[232:235], v[114:129]
	ds_read_b128 v[162:165], v138 offset:0
	ds_read_b128 v[228:231], v139 offset:0
	v_mfma_f32_32x32x16_bf16 v[98:113], v[166:169], v[240:243], v[98:113]
	ds_read_b128 v[236:239], v139 offset:2048
	ds_read_b128 v[204:207], v138 offset:2048
	v_add_u32_e32 v136, s7, v134
	v_add_u32_e32 v137, s7, v135
	v_mfma_f32_32x32x16_bf16 v[82:97], v[208:211], v[232:235], v[82:97]
	ds_read_b128 v[212:215], v138 offset:4096
	ds_read_b128 v[220:223], v138 offset:6144
	v_mfma_f32_32x32x16_bf16 v[66:81], v[208:211], v[240:243], v[66:81]
	v_add_u32_e32 v138, s73, v132
	v_add_u32_e32 v139, s73, v133
	v_mfma_f32_32x32x16_bf16 v[50:65], v[216:219], v[232:235], v[50:65]
	v_mfma_f32_32x32x16_bf16 v[34:49], v[216:219], v[240:243], v[34:49]
	v_mfma_f32_32x32x16_bf16 v[18:33], v[224:227], v[232:235], v[18:33]
	v_mfma_f32_32x32x16_bf16 v[2:17], v[224:227], v[240:243], v[2:17]
	s_setprio 0
	s_waitcnt lgkmcnt(0)
	v_mfma_f32_32x32x16_bf16 v[114:129], v[162:165], v[228:231], v[114:129]
	ds_read_b128 v[166:169], v136 offset:0
	ds_read_b128 v[232:235], v137 offset:0
	s_add_i32 s6, s6, 1
	v_mfma_f32_32x32x16_bf16 v[98:113], v[162:165], v[236:239], v[98:113]
	ds_read_b128 v[240:243], v137 offset:2048
	ds_read_b128 v[208:211], v136 offset:2048
	v_mfma_f32_32x32x16_bf16 v[82:97], v[204:207], v[228:231], v[82:97]
	ds_read_b128 v[216:219], v136 offset:4096
	ds_read_b128 v[224:227], v136 offset:6144
	v_mfma_f32_32x32x16_bf16 v[66:81], v[204:207], v[236:239], v[66:81]
	v_mfma_f32_32x32x16_bf16 v[50:65], v[212:215], v[228:231], v[50:65]
	v_mfma_f32_32x32x16_bf16 v[34:49], v[212:215], v[236:239], v[34:49]
	v_mfma_f32_32x32x16_bf16 v[18:33], v[220:223], v[228:231], v[18:33]
	v_mfma_f32_32x32x16_bf16 v[2:17], v[220:223], v[236:239], v[2:17]
	s_waitcnt vmcnt(0) lgkmcnt(0)
	s_barrier
	s_mov_b32 s7, s73
	s_add_u32 s73, s7, 0x6000
	s_cmp_lt_u32 s73, 0x12000
	s_cselect_b32 s73, s73, 0
	v_mfma_f32_32x32x16_bf16 v[114:129], v[166:169], v[232:235], v[114:129]
	ds_read_b128 v[162:165], v138 offset:0
	ds_read_b128 v[228:231], v139 offset:0
	v_mfma_f32_32x32x16_bf16 v[98:113], v[166:169], v[240:243], v[98:113]
	ds_read_b128 v[236:239], v139 offset:2048
	ds_read_b128 v[204:207], v138 offset:2048
	v_add_u32_e32 v136, s7, v134
	v_add_u32_e32 v137, s7, v135
	v_mfma_f32_32x32x16_bf16 v[82:97], v[208:211], v[232:235], v[82:97]
	ds_read_b128 v[212:215], v138 offset:4096
	ds_read_b128 v[220:223], v138 offset:6144
	v_mfma_f32_32x32x16_bf16 v[66:81], v[208:211], v[240:243], v[66:81]
	v_add_u32_e32 v138, s73, v132
	v_add_u32_e32 v139, s73, v133
	v_mfma_f32_32x32x16_bf16 v[50:65], v[216:219], v[232:235], v[50:65]
	v_mfma_f32_32x32x16_bf16 v[34:49], v[216:219], v[240:243], v[34:49]
	v_mfma_f32_32x32x16_bf16 v[18:33], v[224:227], v[232:235], v[18:33]
	v_mfma_f32_32x32x16_bf16 v[2:17], v[224:227], v[240:243], v[2:17]
	s_setprio 0
	s_waitcnt lgkmcnt(0)
	v_mfma_f32_32x32x16_bf16 v[114:129], v[162:165], v[228:231], v[114:129]
	ds_read_b128 v[166:169], v136 offset:0
	ds_read_b128 v[232:235], v137 offset:0
	s_add_i32 s6, s6, 1
	v_mfma_f32_32x32x16_bf16 v[98:113], v[162:165], v[236:239], v[98:113]
	ds_read_b128 v[240:243], v137 offset:2048
	ds_read_b128 v[208:211], v136 offset:2048
	v_mfma_f32_32x32x16_bf16 v[82:97], v[204:207], v[228:231], v[82:97]
	ds_read_b128 v[216:219], v136 offset:4096
	ds_read_b128 v[224:227], v136 offset:6144
	v_mfma_f32_32x32x16_bf16 v[66:81], v[204:207], v[236:239], v[66:81]
	v_mfma_f32_32x32x16_bf16 v[50:65], v[212:215], v[228:231], v[50:65]
	v_mfma_f32_32x32x16_bf16 v[34:49], v[212:215], v[236:239], v[34:49]
	v_mfma_f32_32x32x16_bf16 v[18:33], v[220:223], v[228:231], v[18:33]
	v_mfma_f32_32x32x16_bf16 v[2:17], v[220:223], v[236:239], v[2:17]
	s_waitcnt lgkmcnt(0)
	v_mfma_f32_32x32x16_bf16 v[114:129], v[166:169], v[232:235], v[114:129]
	v_mfma_f32_32x32x16_bf16 v[98:113], v[166:169], v[240:243], v[98:113]
	v_mfma_f32_32x32x16_bf16 v[82:97], v[208:211], v[232:235], v[82:97]
	v_mfma_f32_32x32x16_bf16 v[66:81], v[208:211], v[240:243], v[66:81]
	v_mfma_f32_32x32x16_bf16 v[50:65], v[216:219], v[232:235], v[50:65]
	v_mfma_f32_32x32x16_bf16 v[34:49], v[216:219], v[240:243], v[34:49]
	v_mfma_f32_32x32x16_bf16 v[18:33], v[224:227], v[232:235], v[18:33]
	v_mfma_f32_32x32x16_bf16 v[2:17], v[224:227], v[240:243], v[2:17]
	s_mov_b32 s14, 31
	s_lshl_b64 s[12:13], s[14:15], 13
	s_movk_i32 s7, 0x7800
	s_movk_i32 s72, 0x6000
	s_mov_b32 s73, 0xc000
	s_setprio 0
	s_movk_i32 s74, 0x104
	s_mov_b32 s75, 0x42ce8ed0
	s_mov_b32 s76, 0xbfb8aa3b
	s_mov_b32 s77, 0x1d730000
	v_mov_b32_e32 v0, v171
	s_barrier
	s_movk_i32 s0, 0x210
	s_waitcnt vmcnt(4)
	v_lshrrev_b32_e32 v130, 1, v0
	v_and_b32_e32 v130, 0xfffffc0, v130
	v_lshrrev_b32_e32 v131, 3, v0
	v_and_or_b32 v130, v131, 4, v130
	v_and_b32_e32 v0, 0x5f, v0
	v_mul_lo_u32 v130, v130, s0
	v_lshl_add_u32 v0, v0, 2, v130
	s_barrier
	ds_write2_b32 v0, v114, v98 offset1:32
	ds_write2_b32 v0, v115, v99 offset0:132 offset1:164
	v_add_u32_e32 v98, 0x400, v0
	ds_write2_b32 v98, v116, v100 offset0:8 offset1:40
	ds_write2_b32 v98, v117, v101 offset0:140 offset1:172
	v_add_u32_e32 v98, 0x1000, v0
	ds_write2_b32 v98, v118, v102 offset0:32 offset1:64
	ds_write2_b32 v98, v119, v103 offset0:164 offset1:196
	v_add_u32_e32 v98, 0x1400, v0
	ds_write2_b32 v98, v120, v104 offset0:40 offset1:72
	ds_write2_b32 v98, v121, v105 offset0:172 offset1:204
	v_add_u32_e32 v98, 0x2000, v0
	ds_write2_b32 v98, v122, v106 offset0:64 offset1:96
	ds_write2_b32 v98, v123, v107 offset0:196 offset1:228
	v_add_u32_e32 v98, 0x2400, v0
	ds_write2_b32 v98, v124, v108 offset0:72 offset1:104
	ds_write2_b32 v98, v125, v109 offset0:204 offset1:236
	v_add_u32_e32 v98, 0x3000, v0
	ds_write2_b32 v98, v126, v110 offset0:96 offset1:128
	v_add_u32_e32 v98, 0x3200, v0
	ds_write2_b32 v98, v127, v111 offset0:100 offset1:132
	v_add_u32_e32 v98, 0x3400, v0
	ds_write2_b32 v98, v128, v112 offset0:104 offset1:136
	v_add_u32_e32 v98, 0x3600, v0
	ds_write2_b32 v98, v129, v113 offset0:108 offset1:140
	v_add_u32_e32 v98, 0x4000, v0
	ds_write2_b32 v98, v82, v66 offset0:128 offset1:160
	v_add_u32_e32 v66, 0x4400, v0
	ds_write2_b32 v66, v83, v67 offset0:4 offset1:36
	ds_write2_b32 v66, v84, v68 offset0:136 offset1:168
	v_add_u32_e32 v66, 0x4800, v0
	ds_write2_b32 v66, v85, v69 offset0:12 offset1:44
	v_add_u32_e32 v66, 0x5000, v0
	ds_write2_b32 v66, v86, v70 offset0:160 offset1:192
	v_add_u32_e32 v66, 0x5400, v0
	ds_write2_b32 v66, v87, v71 offset0:36 offset1:68
	ds_write2_b32 v66, v88, v72 offset0:168 offset1:200
	v_add_u32_e32 v66, 0x5800, v0
	ds_write2_b32 v66, v89, v73 offset0:44 offset1:76
	v_add_u32_e32 v66, 0x6000, v0
	ds_write2_b32 v66, v90, v74 offset0:192 offset1:224
	v_add_u32_e32 v66, 0x6400, v0
	ds_write2_b32 v66, v91, v75 offset0:68 offset1:100
	ds_write2_b32 v66, v92, v76 offset0:200 offset1:232
	v_add_u32_e32 v66, 0x6800, v0
	ds_write2_b32 v66, v93, v77 offset0:76 offset1:108
	v_add_u32_e32 v66, 0x7200, v0
	ds_write2_b32 v66, v94, v78 offset0:96 offset1:128
	v_add_u32_e32 v66, 0x7400, v0
	s_lshr_b32 s14, s42, 2
	ds_write2_b32 v66, v95, v79 offset0:100 offset1:132
	v_add_u32_e32 v66, 0x7600, v0
	v_add_u32_e32 v0, 0x7800, v0
	v_mov_b32_e32 v105, v171
	s_cmp_lt_i32 s14, 14
	s_mov_b64 s[6:7], -1
	ds_write2_b32 v66, v96, v80 offset0:104 offset1:136
	ds_write2_b32 v0, v97, v81 offset0:108 offset1:140
	s_waitcnt lgkmcnt(0)
	s_barrier
	s_cbranch_scc1 .LBB0_439
	s_cmp_gt_i32 s14, 14
	s_cbranch_scc0 .LBB0_436
	s_mov_b64 s[6:7], 0

.Lg588_loop:
	s_setprio 0
	s_waitcnt lgkmcnt(0)
	v_mfma_f32_32x32x16_bf16 v[114:129], v[162:165], v[228:231], v[114:129]
	ds_read_b128 v[166:169], v136 offset:0
	ds_read_b128 v[232:235], v137 offset:0
	s_add_i32 s7, s7, 1
	s_add_i32 s14, s7, 2
	s_lshl_b64 s[12:13], s[14:15], 14
	s_add_u32 s12, s12, s74
	s_addc_u32 s13, s13, s75
	v_mfma_f32_32x32x16_bf16 v[98:113], v[162:165], v[236:239], v[98:113]
	ds_read_b128 v[240:243], v137 offset:2048
	ds_read_b128 v[208:211], v136 offset:2048
	v_mfma_f32_32x32x16_bf16 v[82:97], v[204:207], v[228:231], v[82:97]
	ds_read_b128 v[216:219], v136 offset:4096
	ds_read_b128 v[224:227], v136 offset:6144
	v_mfma_f32_32x32x16_bf16 v[66:81], v[204:207], v[236:239], v[66:81]
	v_mfma_f32_32x32x16_bf16 v[50:65], v[212:215], v[228:231], v[50:65]
	v_mfma_f32_32x32x16_bf16 v[34:49], v[212:215], v[236:239], v[34:49]
	v_mfma_f32_32x32x16_bf16 v[18:33], v[220:223], v[228:231], v[18:33]
	v_mfma_f32_32x32x16_bf16 v[2:17], v[220:223], v[236:239], v[2:17]
	s_waitcnt vmcnt(6) lgkmcnt(0)
	s_barrier
	s_add_u32 m0, s11, s72
	s_mov_b32 s11, s73
	s_add_u32 s73, s11, 0x6000
	s_cmp_lt_u32 s73, 0x12000
	s_cselect_b32 s73, s73, 0
	v_mfma_f32_32x32x16_bf16 v[114:129], v[166:169], v[232:235], v[114:129]
	ds_read_b128 v[162:165], v138 offset:0
	ds_read_b128 v[228:231], v139 offset:0
	v_mfma_f32_32x32x16_bf16 v[98:113], v[166:169], v[240:243], v[98:113]
	ds_read_b128 v[236:239], v139 offset:2048
	ds_read_b128 v[204:207], v138 offset:2048
	v_add_u32_e32 v136, s11, v134
	v_add_u32_e32 v137, s11, v135
	v_mfma_f32_32x32x16_bf16 v[82:97], v[208:211], v[232:235], v[82:97]
	ds_read_b128 v[212:215], v138 offset:4096
	ds_read_b128 v[220:223], v138 offset:6144
	s_setprio 1
	v_mfma_f32_32x32x16_bf16 v[66:81], v[208:211], v[240:243], v[66:81]
	global_load_lds_dwordx4 v140, s[12:13]
	s_add_u32 m0, m0, 0x1000
	s_add_u32 s12, s12, 0x1000
	s_addc_u32 s13, s13, 0
	v_add_u32_e32 v138, s73, v132
	v_add_u32_e32 v139, s73, v133
	v_mfma_f32_32x32x16_bf16 v[50:65], v[216:219], v[232:235], v[50:65]
	global_load_lds_dwordx4 v140, s[12:13]
	s_add_u32 m0, m0, 0x1000
	s_add_u32 s12, s12, 0x1000
	s_addc_u32 s13, s13, 0
	v_mfma_f32_32x32x16_bf16 v[34:49], v[216:219], v[240:243], v[34:49]
	global_load_lds_dwordx4 v140, s[12:13]
	s_add_u32 m0, m0, 0x1000
	s_add_u32 s12, s12, 0x1000
	s_addc_u32 s13, s13, 0
	v_mfma_f32_32x32x16_bf16 v[18:33], v[224:227], v[232:235], v[18:33]
	global_load_lds_dwordx4 v140, s[12:13]
	s_add_u32 m0, m0, 0x1000
	s_lshl_b64 s[12:13], s[14:15], 13
	s_add_u32 s12, s12, s76
	s_addc_u32 s13, s13, s77
	v_mfma_f32_32x32x16_bf16 v[2:17], v[224:227], v[240:243], v[2:17]
	global_load_lds_dwordx4 v140, s[12:13]
	s_add_u32 m0, m0, 0x1000
	s_add_u32 s12, s12, 0x1000
	s_addc_u32 s13, s13, 0
	s_nop 0
	global_load_lds_dwordx4 v140, s[12:13]
	s_cmp_lg_u32 s7, 125
	s_cbranch_scc1 .Lg588_loop
	s_setprio 0
	s_waitcnt lgkmcnt(0)
	v_mfma_f32_32x32x16_bf16 v[114:129], v[162:165], v[228:231], v[114:129]
	ds_read_b128 v[166:169], v136 offset:0
	ds_read_b128 v[232:235], v137 offset:0
	s_add_i32 s7, s7, 1
	v_mfma_f32_32x32x16_bf16 v[98:113], v[162:165], v[236:239], v[98:113]
	ds_read_b128 v[240:243], v137 offset:2048
	ds_read_b128 v[208:211], v136 offset:2048
	v_mfma_f32_32x32x16_bf16 v[82:97], v[204:207], v[228:231], v[82:97]
	ds_read_b128 v[216:219], v136 offset:4096
	ds_read_b128 v[224:227], v136 offset:6144
	v_mfma_f32_32x32x16_bf16 v[66:81], v[204:207], v[236:239], v[66:81]
	v_mfma_f32_32x32x16_bf16 v[50:65], v[212:215], v[228:231], v[50:65]
	v_mfma_f32_32x32x16_bf16 v[34:49], v[212:215], v[236:239], v[34:49]
	v_mfma_f32_32x32x16_bf16 v[18:33], v[220:223], v[228:231], v[18:33]
	v_mfma_f32_32x32x16_bf16 v[2:17], v[220:223], v[236:239], v[2:17]
	s_waitcnt vmcnt(6) lgkmcnt(0)
	s_barrier
	s_mov_b32 s11, s73
	s_add_u32 s73, s11, 0x6000
	s_cmp_lt_u32 s73, 0x12000
	s_cselect_b32 s73, s73, 0
	v_mfma_f32_32x32x16_bf16 v[114:129], v[166:169], v[232:235], v[114:129]
	ds_read_b128 v[162:165], v138 offset:0
	ds_read_b128 v[228:231], v139 offset:0
	v_mfma_f32_32x32x16_bf16 v[98:113], v[166:169], v[240:243], v[98:113]
	ds_read_b128 v[236:239], v139 offset:2048
	ds_read_b128 v[204:207], v138 offset:2048
	v_add_u32_e32 v136, s11, v134
	v_add_u32_e32 v137, s11, v135
	v_mfma_f32_32x32x16_bf16 v[82:97], v[208:211], v[232:235], v[82:97]
	ds_read_b128 v[212:215], v138 offset:4096
	ds_read_b128 v[220:223], v138 offset:6144
	v_mfma_f32_32x32x16_bf16 v[66:81], v[208:211], v[240:243], v[66:81]
	v_add_u32_e32 v138, s73, v132
	v_add_u32_e32 v139, s73, v133
	v_mfma_f32_32x32x16_bf16 v[50:65], v[216:219], v[232:235], v[50:65]
	v_mfma_f32_32x32x16_bf16 v[34:49], v[216:219], v[240:243], v[34:49]
	v_mfma_f32_32x32x16_bf16 v[18:33], v[224:227], v[232:235], v[18:33]
	v_mfma_f32_32x32x16_bf16 v[2:17], v[224:227], v[240:243], v[2:17]
	s_setprio 0
	s_waitcnt lgkmcnt(0)
	v_mfma_f32_32x32x16_bf16 v[114:129], v[162:165], v[228:231], v[114:129]
	ds_read_b128 v[166:169], v136 offset:0
	ds_read_b128 v[232:235], v137 offset:0
	s_add_i32 s7, s7, 1
	v_mfma_f32_32x32x16_bf16 v[98:113], v[162:165], v[236:239], v[98:113]
	ds_read_b128 v[240:243], v137 offset:2048
	ds_read_b128 v[208:211], v136 offset:2048
	v_mfma_f32_32x32x16_bf16 v[82:97], v[204:207], v[228:231], v[82:97]
	ds_read_b128 v[216:219], v136 offset:4096
	ds_read_b128 v[224:227], v136 offset:6144
	v_mfma_f32_32x32x16_bf16 v[66:81], v[204:207], v[236:239], v[66:81]
	v_mfma_f32_32x32x16_bf16 v[50:65], v[212:215], v[228:231], v[50:65]
	v_mfma_f32_32x32x16_bf16 v[34:49], v[212:215], v[236:239], v[34:49]
	v_mfma_f32_32x32x16_bf16 v[18:33], v[220:223], v[228:231], v[18:33]
	v_mfma_f32_32x32x16_bf16 v[2:17], v[220:223], v[236:239], v[2:17]
	s_waitcnt vmcnt(0) lgkmcnt(0)
	s_barrier
	s_mov_b32 s11, s73
	s_add_u32 s73, s11, 0x6000
	s_cmp_lt_u32 s73, 0x12000
	s_cselect_b32 s73, s73, 0
	v_mfma_f32_32x32x16_bf16 v[114:129], v[166:169], v[232:235], v[114:129]
	ds_read_b128 v[162:165], v138 offset:0
	ds_read_b128 v[228:231], v139 offset:0
	v_mfma_f32_32x32x16_bf16 v[98:113], v[166:169], v[240:243], v[98:113]
	ds_read_b128 v[236:239], v139 offset:2048
	ds_read_b128 v[204:207], v138 offset:2048
	v_add_u32_e32 v136, s11, v134
	v_add_u32_e32 v137, s11, v135
	v_mfma_f32_32x32x16_bf16 v[82:97], v[208:211], v[232:235], v[82:97]
	ds_read_b128 v[212:215], v138 offset:4096
	ds_read_b128 v[220:223], v138 offset:6144
	v_mfma_f32_32x32x16_bf16 v[66:81], v[208:211], v[240:243], v[66:81]
	v_add_u32_e32 v138, s73, v132
	v_add_u32_e32 v139, s73, v133
	v_mfma_f32_32x32x16_bf16 v[50:65], v[216:219], v[232:235], v[50:65]
	v_mfma_f32_32x32x16_bf16 v[34:49], v[216:219], v[240:243], v[34:49]
	v_mfma_f32_32x32x16_bf16 v[18:33], v[224:227], v[232:235], v[18:33]
	v_mfma_f32_32x32x16_bf16 v[2:17], v[224:227], v[240:243], v[2:17]
	s_setprio 0
	s_waitcnt lgkmcnt(0)
	v_mfma_f32_32x32x16_bf16 v[114:129], v[162:165], v[228:231], v[114:129]
	ds_read_b128 v[166:169], v136 offset:0
	ds_read_b128 v[232:235], v137 offset:0
	s_add_i32 s7, s7, 1
	v_mfma_f32_32x32x16_bf16 v[98:113], v[162:165], v[236:239], v[98:113]
	ds_read_b128 v[240:243], v137 offset:2048
	ds_read_b128 v[208:211], v136 offset:2048
	v_mfma_f32_32x32x16_bf16 v[82:97], v[204:207], v[228:231], v[82:97]
	ds_read_b128 v[216:219], v136 offset:4096
	ds_read_b128 v[224:227], v136 offset:6144
	v_mfma_f32_32x32x16_bf16 v[66:81], v[204:207], v[236:239], v[66:81]
	v_mfma_f32_32x32x16_bf16 v[50:65], v[212:215], v[228:231], v[50:65]
	v_mfma_f32_32x32x16_bf16 v[34:49], v[212:215], v[236:239], v[34:49]
	v_mfma_f32_32x32x16_bf16 v[18:33], v[220:223], v[228:231], v[18:33]
	v_mfma_f32_32x32x16_bf16 v[2:17], v[220:223], v[236:239], v[2:17]
	s_waitcnt lgkmcnt(0)
	v_mfma_f32_32x32x16_bf16 v[114:129], v[166:169], v[232:235], v[114:129]
	v_mfma_f32_32x32x16_bf16 v[98:113], v[166:169], v[240:243], v[98:113]
	v_mfma_f32_32x32x16_bf16 v[82:97], v[208:211], v[232:235], v[82:97]
	v_mfma_f32_32x32x16_bf16 v[66:81], v[208:211], v[240:243], v[66:81]
	v_mfma_f32_32x32x16_bf16 v[50:65], v[216:219], v[232:235], v[50:65]
	v_mfma_f32_32x32x16_bf16 v[34:49], v[216:219], v[240:243], v[34:49]
	v_mfma_f32_32x32x16_bf16 v[18:33], v[224:227], v[232:235], v[18:33]
	v_mfma_f32_32x32x16_bf16 v[2:17], v[224:227], v[240:243], v[2:17]
	s_mov_b32 s14, 127
	s_lshl_b64 s[12:13], s[14:15], 13
	s_movk_i32 s11, 0x7800
	s_movk_i32 s72, 0x6000
	s_mov_b32 s73, 0xc000
	s_setprio 0
	s_movk_i32 s74, 0x104
	s_mov_b32 s75, 0x42ce8ed0
	s_mov_b32 s76, 0xbfb8aa3b
	s_mov_b32 s77, 0x1d730000
	v_mov_b32_e32 v0, v171
	s_barrier
	s_movk_i32 s0, 0x210
	s_waitcnt vmcnt(4)
	v_lshrrev_b32_e32 v130, 1, v0
	v_and_b32_e32 v130, 0xfffffc0, v130
	v_lshrrev_b32_e32 v131, 3, v0
	v_and_or_b32 v130, v131, 4, v130
	v_and_b32_e32 v0, 0x5f, v0
	v_mul_lo_u32 v130, v130, s0
	v_lshl_add_u32 v0, v0, 2, v130
	s_barrier
	ds_write2_b32 v0, v114, v98 offset1:32
	ds_write2_b32 v0, v115, v99 offset0:132 offset1:164
	v_add_u32_e32 v98, 0x400, v0
	ds_write2_b32 v98, v116, v100 offset0:8 offset1:40
	ds_write2_b32 v98, v117, v101 offset0:140 offset1:172
	v_add_u32_e32 v98, 0x1000, v0
	ds_write2_b32 v98, v118, v102 offset0:32 offset1:64
	ds_write2_b32 v98, v119, v103 offset0:164 offset1:196
	v_add_u32_e32 v98, 0x1400, v0
	ds_write2_b32 v98, v120, v104 offset0:40 offset1:72
	ds_write2_b32 v98, v121, v105 offset0:172 offset1:204
	v_add_u32_e32 v98, 0x2000, v0
	ds_write2_b32 v98, v122, v106 offset0:64 offset1:96
	ds_write2_b32 v98, v123, v107 offset0:196 offset1:228
	v_add_u32_e32 v98, 0x2400, v0
	ds_write2_b32 v98, v124, v108 offset0:72 offset1:104
	ds_write2_b32 v98, v125, v109 offset0:204 offset1:236
	v_add_u32_e32 v98, 0x3000, v0
	ds_write2_b32 v98, v126, v110 offset0:96 offset1:128
	v_add_u32_e32 v98, 0x3200, v0
	ds_write2_b32 v98, v127, v111 offset0:100 offset1:132
	v_add_u32_e32 v98, 0x3400, v0
	ds_write2_b32 v98, v128, v112 offset0:104 offset1:136
	v_add_u32_e32 v98, 0x3600, v0
	ds_write2_b32 v98, v129, v113 offset0:108 offset1:140
	v_add_u32_e32 v98, 0x4000, v0
	ds_write2_b32 v98, v82, v66 offset0:128 offset1:160
	v_add_u32_e32 v66, 0x4400, v0
	ds_write2_b32 v66, v83, v67 offset0:4 offset1:36
	ds_write2_b32 v66, v84, v68 offset0:136 offset1:168
	v_add_u32_e32 v66, 0x4800, v0
	ds_write2_b32 v66, v85, v69 offset0:12 offset1:44
	v_add_u32_e32 v66, 0x5000, v0
	s_lshl_b32 s10, s10, 8
	ds_write2_b32 v66, v86, v70 offset0:160 offset1:192
	v_add_u32_e32 v66, 0x5400, v0
	s_lshl_b32 s11, s6, 7
	ds_write2_b32 v66, v87, v71 offset0:36 offset1:68
	ds_write2_b32 v66, v88, v72 offset0:168 offset1:200
	v_add_u32_e32 v66, 0x5800, v0
	s_add_i32 s6, s10, 0xffffe000
	ds_write2_b32 v66, v89, v73 offset0:44 offset1:76
	v_add_u32_e32 v66, 0x6000, v0
	s_lshr_b32 s6, s6, 12
	ds_write2_b32 v66, v90, v74 offset0:192 offset1:224
	v_add_u32_e32 v66, 0x6400, v0
	s_mulk_i32 s6, 0x1800
	ds_write2_b32 v66, v91, v75 offset0:68 offset1:100
	ds_write2_b32 v66, v92, v76 offset0:200 offset1:232
	v_add_u32_e32 v66, 0x6800, v0
	s_addk_i32 s6, 0x1800
	ds_write2_b32 v66, v93, v77 offset0:76 offset1:108
	v_add_u32_e32 v66, 0x7200, v0
	s_cmp_gt_u32 s9, 31
	ds_write2_b32 v66, v94, v78 offset0:96 offset1:128
	v_add_u32_e32 v66, 0x7400, v0
	s_cselect_b32 s14, s6, 0
	ds_write2_b32 v66, v95, v79 offset0:100 offset1:132
	v_add_u32_e32 v66, 0x7600, v0
	v_add_u32_e32 v0, 0x7800, v0
	v_mov_b32_e32 v84, v171
	s_lshl_b64 s[6:7], s[14:15], 2
	ds_write2_b32 v66, v96, v80 offset0:104 offset1:136
	ds_write2_b32 v0, v97, v81 offset0:108 offset1:140
	s_waitcnt lgkmcnt(0)
	s_barrier
	s_add_u32 s6, s61, s6
	v_lshlrev_b32_e32 v0, 3, v84
	v_and_b32_e32 v0, 0x78, v0
	s_addc_u32 s7, s53, s7
	v_or_b32_e32 v0, s11, v0
	s_add_u32 s6, s6, 0x1d645000
	s_addc_u32 s7, s7, 0
	v_lshlrev_b64 v[82:83], 2, v[0:1]
	v_lshl_add_u64 v[70:71], s[6:7], 0, v[82:83]
	v_lshl_add_u64 v[78:79], s[4:5], 0, v[82:83]
	global_load_dwordx4 v[66:69], v[70:71], off offset:16
	s_nop 0
	global_load_dwordx4 v[70:73], v[70:71], off
	s_nop 0
	global_load_dwordx4 v[74:77], v[78:79], off offset:16
	s_nop 0
	global_load_dwordx4 v[78:81], v[78:79], off
	v_ashrrev_i32_e32 v0, 4, v84
	v_mul_lo_u32 v85, v0, s0
	v_and_b32_e32 v84, 15, v84
	s_mov_b32 s9, 0
	v_lshl_add_u64 v[82:83], s[56:57], 0, v[82:83]
	v_lshl_add_u32 v84, v84, 5, v85
	v_lshlrev_b32_e32 v85, 1, v0
